# in-proj and FF1 K-loops: LDS-DMA loads of the long load segments (phases 1,3,5,7) issued between MFMAs of the same phase
# baseline (speedup 1.0000x reference)
; #define PG8_STAGE(bufoff, gbase, voff) do { _Pragma("unroll") for (int _i = 0; _i < 2; ++_i) \
;         __builtin_amdgcn_global_load_lds((const unsigned*)((const char*)(gbase) + (voff)[_i]), (LAS unsigned*)(lds + (bufoff) + ldsw + _i * 8192), 16, 0, 0); } while (0)
; #define PG8_LDA(dst, b, h) do { _Pragma("unroll") for (int m = 0; m < 4; ++m) _Pragma("unroll") for (int k = 0; k < 2; ++k) dst[m][k] = *(const LAS bf16x8*)(lds + PG8_SA(b, h) + aoff + m * 2048 + k * 1024); } while (0)
; #define PG8_LDB(dst, b, h) do { _Pragma("unroll") for (int n = 0; n < 2; ++n) _Pragma("unroll") for (int k = 0; k < 2; ++k) dst[n][k] = *(const LAS bf16x8*)(lds + PG8_SB(b, h) + boff + n * 2048 + k * 1024); } while (0)
; #define PG8_MMA(ai, bj, At, Bt) do { __builtin_amdgcn_s_setprio(1); _Pragma("unroll") for (int m = 0; m < 4; ++m) _Pragma("unroll") for (int n = 0; n < 2; ++n) _Pragma("unroll") for (int k = 0; k < 2; ++k) \
;         acc[ai][bj][m][n] = __builtin_amdgcn_mfma_f32_16x16x32_bf16(Bt[n][k], At[m][k], acc[ai][bj][m][n], 0, 0, 0); __builtin_amdgcn_s_setprio(0); } while (0)
; #define PG8_WAIT_V(n) asm volatile("s_waitcnt vmcnt(" #n ")" ::: "memory")
; #define PG8_WAIT_L(n) asm volatile("s_waitcnt lgkmcnt(" #n ")" ::: "memory")
; #define PG8_BAR __builtin_amdgcn_s_barrier()
; #define PG8_SCHED __builtin_amdgcn_sched_barrier(0)
; template <class Epi, class Sched>
; __device__ __forceinline__ void gemm_phase(LAS unsigned char* lds, const Gemm g, const Sched& S, const Epi& E) {
;     ...
;             PG8_LDB(B0, 0, 0); PG8_SCHED; PG8_LDA(At, 0, 0); PG8_STAGE(PG8_SA(1, 1), a1 + hstep, voffA);
;             PG8_WAIT_L(8); PG8_BAR; PG8_WAIT_L(0); PG8_MMA(0, 0, At, B0); PG8_BAR; PG8_SCHED;
;             PG8_LDB(B1, 0, 1); PG8_STAGE(PG8_SB(0, 0), b2, voffB);
;             PG8_BAR; PG8_WAIT_L(0); PG8_MMA(0, 1, At, B1); PG8_BAR;
;             PG8_LDA(At, 0, 1); PG8_STAGE(PG8_SA(0, 0), a2, voffA);
;             PG8_BAR; PG8_WAIT_L(0); PG8_MMA(1, 0, At, B0); PG8_BAR; PG8_SCHED;
;             PG8_STAGE(PG8_SB(0, 1), b2 + hstep, voffB);
;             PG8_WAIT_V(6); PG8_BAR; PG8_MMA(1, 1, At, B1); PG8_BAR;
.LBB0_342:
	s_nop 0
	v_add_u32_e32 v158, s42, v147
	ds_read_b128 v[142:145], v158
	ds_read_b128 v[150:153], v158 offset:1024
	ds_read_b128 v[154:157], v158 offset:2048
	ds_read_b128 v[158:161], v158 offset:3072
	s_add_u32 s18, s16, 0xfff80080
	s_addc_u32 s19, s17, -1
	s_cmp_eq_u32 s38, 28
	s_cselect_b32 s21, s11, s19
	s_cselect_b32 s20, s34, s18
	s_cselect_b32 s19, s9, s37
	s_cselect_b32 s18, s35, s36
	ds_read_b128 v[162:165], v149
	ds_read_b128 v[166:169], v149 offset:1024
	ds_read_b128 v[170:173], v149 offset:2048
	ds_read_b128 v[174:177], v149 offset:3072
	ds_read_b128 v[178:181], v149 offset:4096
	ds_read_b128 v[182:185], v149 offset:5120
	ds_read_b128 v[186:189], v149 offset:6144
	ds_read_b128 v[190:193], v149 offset:7168
	s_waitcnt lgkmcnt(8)
	s_barrier
	s_waitcnt lgkmcnt(0)
	v_mfma_f32_16x16x32_bf16 v[126:129], v[142:145], v[162:165], v[126:129]
	v_mfma_f32_16x16x32_bf16 v[122:125], v[154:157], v[162:165], v[122:125]
	v_mfma_f32_16x16x32_bf16 v[114:117], v[142:145], v[170:173], v[114:117]
	v_mfma_f32_16x16x32_bf16 v[106:109], v[154:157], v[170:173], v[106:109]
	s_add_i32 m0, s24, 0xc000
	v_mfma_f32_16x16x32_bf16 v[98:101], v[142:145], v[178:181], v[98:101]
	global_load_lds_dwordx4 v138, s[16:17]
	v_mfma_f32_16x16x32_bf16 v[90:93], v[154:157], v[178:181], v[90:93]
	v_mfma_f32_16x16x32_bf16 v[82:85], v[142:145], v[186:189], v[82:85]
	v_mfma_f32_16x16x32_bf16 v[74:77], v[154:157], v[186:189], v[74:77]
	v_mfma_f32_16x16x32_bf16 v[126:129], v[150:153], v[166:169], v[126:129]
	v_mfma_f32_16x16x32_bf16 v[122:125], v[158:161], v[166:169], v[122:125]
	s_add_i32 m0, s24, 0xe000
	v_mfma_f32_16x16x32_bf16 v[114:117], v[150:153], v[174:177], v[114:117]
	global_load_lds_dwordx4 v140, s[16:17]
	v_mfma_f32_16x16x32_bf16 v[106:109], v[158:161], v[174:177], v[106:109]
	v_mfma_f32_16x16x32_bf16 v[98:101], v[150:153], v[182:185], v[98:101]
	v_mfma_f32_16x16x32_bf16 v[90:93], v[158:161], v[182:185], v[90:93]
	v_mfma_f32_16x16x32_bf16 v[82:85], v[150:153], v[190:193], v[82:85]
	v_mfma_f32_16x16x32_bf16 v[74:77], v[158:161], v[190:193], v[74:77]
	s_barrier
	s_add_i32 s39, 0, 0x14000
	s_add_i32 s40, s42, s23
	v_add_u32_e32 v206, s39, v147
	s_mov_b32 m0, s40
	ds_read_b128 v[194:197], v206
	ds_read_b128 v[198:201], v206 offset:1024
	ds_read_b128 v[202:205], v206 offset:2048
	ds_read_b128 v[206:209], v206 offset:3072
	global_load_lds_dwordx4 v0, s[18:19]
	s_add_i32 m0, s40, 0x2000
	s_nop 0
	global_load_lds_dwordx4 v130, s[18:19]
	s_barrier
	s_waitcnt lgkmcnt(0)
	v_mfma_f32_16x16x32_bf16 v[118:121], v[194:197], v[162:165], v[118:121]
	v_mfma_f32_16x16x32_bf16 v[110:113], v[202:205], v[162:165], v[110:113]
	v_mfma_f32_16x16x32_bf16 v[102:105], v[194:197], v[170:173], v[102:105]
	v_mfma_f32_16x16x32_bf16 v[94:97], v[202:205], v[170:173], v[94:97]
	v_mfma_f32_16x16x32_bf16 v[86:89], v[194:197], v[178:181], v[86:89]
	v_mfma_f32_16x16x32_bf16 v[78:81], v[202:205], v[178:181], v[78:81]
	v_mfma_f32_16x16x32_bf16 v[70:73], v[194:197], v[186:189], v[70:73]
	v_mfma_f32_16x16x32_bf16 v[66:69], v[202:205], v[186:189], v[66:69]
	v_mfma_f32_16x16x32_bf16 v[118:121], v[198:201], v[166:169], v[118:121]
	v_mfma_f32_16x16x32_bf16 v[110:113], v[206:209], v[166:169], v[110:113]
	v_mfma_f32_16x16x32_bf16 v[102:105], v[198:201], v[174:177], v[102:105]
	v_mfma_f32_16x16x32_bf16 v[94:97], v[206:209], v[174:177], v[94:97]
	v_mfma_f32_16x16x32_bf16 v[86:89], v[198:201], v[182:185], v[86:89]
	v_mfma_f32_16x16x32_bf16 v[78:81], v[206:209], v[182:185], v[78:81]
	v_mfma_f32_16x16x32_bf16 v[70:73], v[198:201], v[190:193], v[70:73]
	v_mfma_f32_16x16x32_bf16 v[66:69], v[206:209], v[190:193], v[66:69]
	s_add_u32 s44, s20, 0x80
	s_addc_u32 s45, s21, 0
	s_barrier
	ds_read_b128 v[162:165], v149 offset:16384
	ds_read_b128 v[166:169], v149 offset:17408
	ds_read_b128 v[170:173], v149 offset:18432
	ds_read_b128 v[174:177], v149 offset:19456
	ds_read_b128 v[178:181], v149 offset:20480
	ds_read_b128 v[182:185], v149 offset:21504
	ds_read_b128 v[186:189], v149 offset:22528
	ds_read_b128 v[190:193], v149 offset:23552
	s_barrier
	s_waitcnt lgkmcnt(0)
	v_mfma_f32_16x16x32_bf16 v[62:65], v[142:145], v[162:165], v[62:65]
	v_mfma_f32_16x16x32_bf16 v[58:61], v[154:157], v[162:165], v[58:61]
	v_mfma_f32_16x16x32_bf16 v[50:53], v[142:145], v[170:173], v[50:53]
	v_mfma_f32_16x16x32_bf16 v[42:45], v[154:157], v[170:173], v[42:45]
	s_mov_b32 m0, s24
	v_mfma_f32_16x16x32_bf16 v[34:37], v[142:145], v[178:181], v[34:37]
	global_load_lds_dwordx4 v134, s[20:21]
	v_mfma_f32_16x16x32_bf16 v[26:29], v[154:157], v[178:181], v[26:29]
	v_mfma_f32_16x16x32_bf16 v[18:21], v[142:145], v[186:189], v[18:21]
	v_mfma_f32_16x16x32_bf16 v[10:13], v[154:157], v[186:189], v[10:13]
	v_mfma_f32_16x16x32_bf16 v[62:65], v[150:153], v[166:169], v[62:65]
	v_mfma_f32_16x16x32_bf16 v[58:61], v[158:161], v[166:169], v[58:61]
	s_mov_b32 m0, s25
	v_mfma_f32_16x16x32_bf16 v[50:53], v[150:153], v[174:177], v[50:53]
	global_load_lds_dwordx4 v132, s[20:21]
	v_mfma_f32_16x16x32_bf16 v[42:45], v[158:161], v[174:177], v[42:45]
	v_mfma_f32_16x16x32_bf16 v[34:37], v[150:153], v[182:185], v[34:37]
	v_mfma_f32_16x16x32_bf16 v[26:29], v[158:161], v[182:185], v[26:29]
	v_mfma_f32_16x16x32_bf16 v[18:21], v[150:153], v[190:193], v[18:21]
	v_mfma_f32_16x16x32_bf16 v[10:13], v[158:161], v[190:193], v[10:13]
	s_barrier
	s_add_u32 s40, s18, 0x80000
	s_addc_u32 s41, s19, 0
	s_add_i32 s39, s39, s23
	s_mov_b32 m0, s39
	s_nop 0
	global_load_lds_dwordx4 v0, s[40:41]
	s_add_i32 m0, s39, 0x2000
	s_nop 0
	global_load_lds_dwordx4 v130, s[40:41]
	s_waitcnt vmcnt(6)
	s_barrier
; #define PG8_STAGE(bufoff, gbase, voff) do { _Pragma("unroll") for (int _i = 0; _i < 2; ++_i) \
;         __builtin_amdgcn_global_load_lds((const unsigned*)((const char*)(gbase) + (voff)[_i]), (LAS unsigned*)(lds + (bufoff) + ldsw + _i * 8192), 16, 0, 0); } while (0)
; #define PG8_LDA(dst, b, h) do { _Pragma("unroll") for (int m = 0; m < 4; ++m) _Pragma("unroll") for (int k = 0; k < 2; ++k) dst[m][k] = *(const LAS bf16x8*)(lds + PG8_SA(b, h) + aoff + m * 2048 + k * 1024); } while (0)
; #define PG8_LDB(dst, b, h) do { _Pragma("unroll") for (int n = 0; n < 2; ++n) _Pragma("unroll") for (int k = 0; k < 2; ++k) dst[n][k] = *(const LAS bf16x8*)(lds + PG8_SB(b, h) + boff + n * 2048 + k * 1024); } while (0)
; #define PG8_MMA(ai, bj, At, Bt) do { __builtin_amdgcn_s_setprio(1); _Pragma("unroll") for (int m = 0; m < 4; ++m) _Pragma("unroll") for (int n = 0; n < 2; ++n) _Pragma("unroll") for (int k = 0; k < 2; ++k) \
;         acc[ai][bj][m][n] = __builtin_amdgcn_mfma_f32_16x16x32_bf16(Bt[n][k], At[m][k], acc[ai][bj][m][n], 0, 0, 0); __builtin_amdgcn_s_setprio(0); } while (0)
; #define PG8_WAIT_V(n) asm volatile("s_waitcnt vmcnt(" #n ")" ::: "memory")
; #define PG8_WAIT_L(n) asm volatile("s_waitcnt lgkmcnt(" #n ")" ::: "memory")
; #define PG8_BAR __builtin_amdgcn_s_barrier()
; #define PG8_SCHED __builtin_amdgcn_sched_barrier(0)
; template <class Epi, class Sched>
; __device__ __forceinline__ void gemm_phase(LAS unsigned char* lds, const Gemm g, const Sched& S, const Epi& E) {
;     ...
;             PG8_WAIT_V(6); PG8_BAR; PG8_MMA(1, 1, At, B1); PG8_BAR;
;             PG8_LDB(B0, 1, 0); PG8_SCHED; PG8_LDA(At, 1, 0); PG8_STAGE(PG8_SA(0, 1), a2 + hstep, voffA);
;             PG8_WAIT_L(8); PG8_BAR; PG8_WAIT_L(0); PG8_MMA(0, 0, At, B0); PG8_BAR; PG8_SCHED;
;             PG8_LDB(B1, 1, 1); PG8_STAGE(PG8_SB(1, 0), b3, voffB);
;             PG8_BAR; PG8_WAIT_L(0); PG8_MMA(0, 1, At, B1); PG8_BAR;
;             PG8_LDA(At, 1, 1); PG8_STAGE(PG8_SA(1, 0), a3, voffA);
;             PG8_BAR; PG8_WAIT_L(0); PG8_MMA(1, 0, At, B0); PG8_BAR; PG8_SCHED;
	v_mfma_f32_16x16x32_bf16 v[54:57], v[194:197], v[162:165], v[54:57]
	v_mfma_f32_16x16x32_bf16 v[46:49], v[202:205], v[162:165], v[46:49]
	v_mfma_f32_16x16x32_bf16 v[38:41], v[194:197], v[170:173], v[38:41]
	v_mfma_f32_16x16x32_bf16 v[30:33], v[202:205], v[170:173], v[30:33]
	v_mfma_f32_16x16x32_bf16 v[22:25], v[194:197], v[178:181], v[22:25]
	v_mfma_f32_16x16x32_bf16 v[14:17], v[202:205], v[178:181], v[14:17]
	v_mfma_f32_16x16x32_bf16 v[6:9], v[194:197], v[186:189], v[6:9]
	v_mfma_f32_16x16x32_bf16 v[2:5], v[202:205], v[186:189], v[2:5]
	v_mfma_f32_16x16x32_bf16 v[54:57], v[198:201], v[166:169], v[54:57]
	v_mfma_f32_16x16x32_bf16 v[46:49], v[206:209], v[166:169], v[46:49]
	v_mfma_f32_16x16x32_bf16 v[38:41], v[198:201], v[174:177], v[38:41]
	v_mfma_f32_16x16x32_bf16 v[30:33], v[206:209], v[174:177], v[30:33]
	v_mfma_f32_16x16x32_bf16 v[22:25], v[198:201], v[182:185], v[22:25]
	v_mfma_f32_16x16x32_bf16 v[14:17], v[206:209], v[182:185], v[14:17]
	v_mfma_f32_16x16x32_bf16 v[6:9], v[198:201], v[190:193], v[6:9]
	v_mfma_f32_16x16x32_bf16 v[2:5], v[206:209], v[190:193], v[2:5]
	s_add_i32 s39, 0, 0x18000
	v_add_u32_e32 v158, s39, v147
	s_barrier
	ds_read_b128 v[142:145], v158
	ds_read_b128 v[150:153], v158 offset:1024
	ds_read_b128 v[154:157], v158 offset:2048
	ds_read_b128 v[158:161], v158 offset:3072
	s_add_u32 s20, s20, 0x80000
	s_addc_u32 s21, s21, 0
	ds_read_b128 v[162:165], v149 offset:32768
	ds_read_b128 v[166:169], v149 offset:33792
	ds_read_b128 v[170:173], v149 offset:34816
	ds_read_b128 v[174:177], v149 offset:35840
	ds_read_b128 v[178:181], v149 offset:36864
	ds_read_b128 v[182:185], v149 offset:37888
	ds_read_b128 v[186:189], v149 offset:38912
	ds_read_b128 v[190:193], v149 offset:39936
	s_waitcnt lgkmcnt(8)
	s_barrier
	s_waitcnt lgkmcnt(0)
	v_mfma_f32_16x16x32_bf16 v[126:129], v[142:145], v[162:165], v[126:129]
	v_mfma_f32_16x16x32_bf16 v[122:125], v[154:157], v[162:165], v[122:125]
	v_mfma_f32_16x16x32_bf16 v[114:117], v[142:145], v[170:173], v[114:117]
	v_mfma_f32_16x16x32_bf16 v[106:109], v[154:157], v[170:173], v[106:109]
	s_mov_b32 m0, s26
	v_mfma_f32_16x16x32_bf16 v[98:101], v[142:145], v[178:181], v[98:101]
	global_load_lds_dwordx4 v134, s[20:21]
	v_mfma_f32_16x16x32_bf16 v[90:93], v[154:157], v[178:181], v[90:93]
	v_mfma_f32_16x16x32_bf16 v[82:85], v[142:145], v[186:189], v[82:85]
	v_mfma_f32_16x16x32_bf16 v[74:77], v[154:157], v[186:189], v[74:77]
	v_mfma_f32_16x16x32_bf16 v[126:129], v[150:153], v[166:169], v[126:129]
	v_mfma_f32_16x16x32_bf16 v[122:125], v[158:161], v[166:169], v[122:125]
	s_mov_b32 m0, s27
	v_mfma_f32_16x16x32_bf16 v[114:117], v[150:153], v[174:177], v[114:117]
	global_load_lds_dwordx4 v132, s[20:21]
	v_mfma_f32_16x16x32_bf16 v[106:109], v[158:161], v[174:177], v[106:109]
	v_mfma_f32_16x16x32_bf16 v[98:101], v[150:153], v[182:185], v[98:101]
	v_mfma_f32_16x16x32_bf16 v[90:93], v[158:161], v[182:185], v[90:93]
	v_mfma_f32_16x16x32_bf16 v[82:85], v[150:153], v[190:193], v[82:85]
	v_mfma_f32_16x16x32_bf16 v[74:77], v[158:161], v[190:193], v[74:77]
	s_barrier
	s_add_i32 s20, 0, 0x1c000
	s_add_i32 s21, s39, s23
	v_add_u32_e32 v206, s20, v147
	s_add_u32 s40, s18, 0x80
	s_addc_u32 s41, s19, 0
	s_mov_b32 m0, s21
	ds_read_b128 v[194:197], v206
	ds_read_b128 v[198:201], v206 offset:1024
	ds_read_b128 v[202:205], v206 offset:2048
	ds_read_b128 v[206:209], v206 offset:3072
	global_load_lds_dwordx4 v0, s[40:41]
	s_add_i32 m0, s21, 0x2000
	s_nop 0
	global_load_lds_dwordx4 v130, s[40:41]
	s_barrier
	s_waitcnt lgkmcnt(0)
	v_mfma_f32_16x16x32_bf16 v[118:121], v[194:197], v[162:165], v[118:121]
	v_mfma_f32_16x16x32_bf16 v[110:113], v[202:205], v[162:165], v[110:113]
	v_mfma_f32_16x16x32_bf16 v[102:105], v[194:197], v[170:173], v[102:105]
	v_mfma_f32_16x16x32_bf16 v[94:97], v[202:205], v[170:173], v[94:97]
	v_mfma_f32_16x16x32_bf16 v[86:89], v[194:197], v[178:181], v[86:89]
	v_mfma_f32_16x16x32_bf16 v[78:81], v[202:205], v[178:181], v[78:81]
	v_mfma_f32_16x16x32_bf16 v[70:73], v[194:197], v[186:189], v[70:73]
	v_mfma_f32_16x16x32_bf16 v[66:69], v[202:205], v[186:189], v[66:69]
	v_mfma_f32_16x16x32_bf16 v[118:121], v[198:201], v[166:169], v[118:121]
	v_mfma_f32_16x16x32_bf16 v[110:113], v[206:209], v[166:169], v[110:113]
	v_mfma_f32_16x16x32_bf16 v[102:105], v[198:201], v[174:177], v[102:105]
	v_mfma_f32_16x16x32_bf16 v[94:97], v[206:209], v[174:177], v[94:97]
	v_mfma_f32_16x16x32_bf16 v[86:89], v[198:201], v[182:185], v[86:89]
	v_mfma_f32_16x16x32_bf16 v[78:81], v[206:209], v[182:185], v[78:81]
	v_mfma_f32_16x16x32_bf16 v[70:73], v[198:201], v[190:193], v[70:73]
	v_mfma_f32_16x16x32_bf16 v[66:69], v[206:209], v[190:193], v[66:69]
	s_barrier
; #define PG8_STAGE(bufoff, gbase, voff) do { _Pragma("unroll") for (int _i = 0; _i < 2; ++_i) \
;         __builtin_amdgcn_global_load_lds((const unsigned*)((const char*)(gbase) + (voff)[_i]), (LAS unsigned*)(lds + (bufoff) + ldsw + _i * 8192), 16, 0, 0); } while (0)
; #define PG8_LDA(dst, b, h) do { _Pragma("unroll") for (int m = 0; m < 4; ++m) _Pragma("unroll") for (int k = 0; k < 2; ++k) dst[m][k] = *(const LAS bf16x8*)(lds + PG8_SA(b, h) + aoff + m * 2048 + k * 1024); } while (0)
; #define PG8_MMA(ai, bj, At, Bt) do { __builtin_amdgcn_s_setprio(1); _Pragma("unroll") for (int m = 0; m < 4; ++m) _Pragma("unroll") for (int n = 0; n < 2; ++n) _Pragma("unroll") for (int k = 0; k < 2; ++k) \
;         acc[ai][bj][m][n] = __builtin_amdgcn_mfma_f32_16x16x32_bf16(Bt[n][k], At[m][k], acc[ai][bj][m][n], 0, 0, 0); __builtin_amdgcn_s_setprio(0); } while (0)
; #define PG8_WAIT_V(n) asm volatile("s_waitcnt vmcnt(" #n ")" ::: "memory")
; #define PG8_WAIT_L(n) asm volatile("s_waitcnt lgkmcnt(" #n ")" ::: "memory")
; #define PG8_BAR __builtin_amdgcn_s_barrier()
; #define PG8_SCHED __builtin_amdgcn_sched_barrier(0)
; template <class Epi, class Sched>
; __device__ __forceinline__ void gemm_phase(LAS unsigned char* lds, const Gemm g, const Sched& S, const Epi& E) {
;     ...
;             PG8_LDA(At, 1, 1); PG8_STAGE(PG8_SA(1, 0), a3, voffA);
;             PG8_BAR; PG8_WAIT_L(0); PG8_MMA(1, 0, At, B0); PG8_BAR; PG8_SCHED;
;             PG8_STAGE(PG8_SB(1, 1), b3 + hstep, voffB);
;             PG8_WAIT_V(6); PG8_BAR; PG8_MMA(1, 1, At, B1); PG8_BAR;
;     __device__ __forceinline__ void operator()(const f32x4 (&acc)[2][2][4][2], const pg8::Unit& u, int wr, int wc, int fr, int fq) const {
;     ...
;                     if (ACT == 0) { if (u.pn == (C_G / 256) && bj == 0 && wc == 0 && fq < 2) { float* gp = gate + (size_t)row * 16 + 8 * fq; *(f32x4*)gp = v0; *(f32x4*)(gp + 4) = v1; } }
	ds_read_b128 v[162:165], v149 offset:49152
	ds_read_b128 v[166:169], v149 offset:50176
	ds_read_b128 v[170:173], v149 offset:51200
	ds_read_b128 v[174:177], v149 offset:52224
	ds_read_b128 v[178:181], v149 offset:53248
	ds_read_b128 v[182:185], v149 offset:54272
	ds_read_b128 v[186:189], v149 offset:55296
	ds_read_b128 v[190:193], v149 offset:56320
	s_barrier
	s_waitcnt lgkmcnt(0)
	v_mfma_f32_16x16x32_bf16 v[62:65], v[142:145], v[162:165], v[62:65]
	v_mfma_f32_16x16x32_bf16 v[58:61], v[154:157], v[162:165], v[58:61]
	v_mfma_f32_16x16x32_bf16 v[50:53], v[142:145], v[170:173], v[50:53]
	v_mfma_f32_16x16x32_bf16 v[42:45], v[154:157], v[170:173], v[42:45]
	s_mov_b32 m0, s28
	v_mfma_f32_16x16x32_bf16 v[34:37], v[142:145], v[178:181], v[34:37]
	global_load_lds_dwordx4 v134, s[44:45]
	v_mfma_f32_16x16x32_bf16 v[26:29], v[154:157], v[178:181], v[26:29]
	v_mfma_f32_16x16x32_bf16 v[18:21], v[142:145], v[186:189], v[18:21]
	v_mfma_f32_16x16x32_bf16 v[10:13], v[154:157], v[186:189], v[10:13]
	v_mfma_f32_16x16x32_bf16 v[62:65], v[150:153], v[166:169], v[62:65]
	v_mfma_f32_16x16x32_bf16 v[58:61], v[158:161], v[166:169], v[58:61]
	s_mov_b32 m0, s29
	v_mfma_f32_16x16x32_bf16 v[50:53], v[150:153], v[174:177], v[50:53]
	global_load_lds_dwordx4 v132, s[44:45]
	v_mfma_f32_16x16x32_bf16 v[42:45], v[158:161], v[174:177], v[42:45]
	v_mfma_f32_16x16x32_bf16 v[34:37], v[150:153], v[182:185], v[34:37]
	v_mfma_f32_16x16x32_bf16 v[26:29], v[158:161], v[182:185], v[26:29]
	v_mfma_f32_16x16x32_bf16 v[18:21], v[150:153], v[190:193], v[18:21]
	v_mfma_f32_16x16x32_bf16 v[10:13], v[158:161], v[190:193], v[10:13]
	s_barrier
	s_add_u32 s18, s18, 0x80080
	s_addc_u32 s19, s19, 0
	s_add_i32 s20, s20, s23
	s_mov_b32 m0, s20
	s_nop 0
	global_load_lds_dwordx4 v0, s[18:19]
	s_add_i32 m0, s20, 0x2000
	s_nop 0
	global_load_lds_dwordx4 v130, s[18:19]
	s_waitcnt vmcnt(6)
	s_barrier
	v_mfma_f32_16x16x32_bf16 v[54:57], v[194:197], v[162:165], v[54:57]
	v_mfma_f32_16x16x32_bf16 v[46:49], v[202:205], v[162:165], v[46:49]
	v_mfma_f32_16x16x32_bf16 v[38:41], v[194:197], v[170:173], v[38:41]
	v_mfma_f32_16x16x32_bf16 v[30:33], v[202:205], v[170:173], v[30:33]
	v_mfma_f32_16x16x32_bf16 v[22:25], v[194:197], v[178:181], v[22:25]
	v_mfma_f32_16x16x32_bf16 v[14:17], v[202:205], v[178:181], v[14:17]
	v_mfma_f32_16x16x32_bf16 v[6:9], v[194:197], v[186:189], v[6:9]
	v_mfma_f32_16x16x32_bf16 v[2:5], v[202:205], v[186:189], v[2:5]
	v_mfma_f32_16x16x32_bf16 v[54:57], v[198:201], v[166:169], v[54:57]
	v_mfma_f32_16x16x32_bf16 v[46:49], v[206:209], v[166:169], v[46:49]
	v_mfma_f32_16x16x32_bf16 v[38:41], v[198:201], v[174:177], v[38:41]
	v_mfma_f32_16x16x32_bf16 v[30:33], v[206:209], v[174:177], v[30:33]
	v_mfma_f32_16x16x32_bf16 v[22:25], v[198:201], v[182:185], v[22:25]
	v_mfma_f32_16x16x32_bf16 v[14:17], v[206:209], v[182:185], v[14:17]
	v_mfma_f32_16x16x32_bf16 v[6:9], v[198:201], v[190:193], v[6:9]
	v_mfma_f32_16x16x32_bf16 v[2:5], v[206:209], v[190:193], v[2:5]
	s_add_i32 s38, s38, 2
	s_add_u32 s16, s16, 0x100
	s_addc_u32 s17, s17, 0
	s_add_u32 s36, s36, 0x100
	s_addc_u32 s37, s37, 0
	s_cmp_gt_u32 s38, 29
	s_barrier
	s_cbranch_scc0 .LBB0_342
	s_cmp_eq_u32 s3, 18
	s_cselect_b64 s[16:17], -1, 0
	v_lshl_add_u32 v142, s31, 8, v146
	s_and_b64 s[16:17], s[6:7], s[16:17]
	v_ashrrev_i32_e32 v143, 31, v142
	s_and_b64 s[16:17], s[16:17], s[0:1]
	s_and_saveexec_b64 s[18:19], s[16:17]
	s_cbranch_execz .LBB0_345
	v_lshlrev_b64 v[144:145], 6, v[142:143]
	v_lshl_add_u64 v[144:145], v[136:137], 0, v[144:145]
	global_store_dwordx4 v[144:145], v[126:129], off
	global_store_dwordx4 v[144:145], v[122:125], off offset:16

; #define PG8_STAGE(bufoff, gbase, voff) do { _Pragma("unroll") for (int _i = 0; _i < 2; ++_i) \
;         __builtin_amdgcn_global_load_lds((const unsigned*)((const char*)(gbase) + (voff)[_i]), (LAS unsigned*)(lds + (bufoff) + ldsw + _i * 8192), 16, 0, 0); } while (0)
; #define PG8_LDA(dst, b, h) do { _Pragma("unroll") for (int m = 0; m < 4; ++m) _Pragma("unroll") for (int k = 0; k < 2; ++k) dst[m][k] = *(const LAS bf16x8*)(lds + PG8_SA(b, h) + aoff + m * 2048 + k * 1024); } while (0)
; #define PG8_LDB(dst, b, h) do { _Pragma("unroll") for (int n = 0; n < 2; ++n) _Pragma("unroll") for (int k = 0; k < 2; ++k) dst[n][k] = *(const LAS bf16x8*)(lds + PG8_SB(b, h) + boff + n * 2048 + k * 1024); } while (0)
; #define PG8_MMA(ai, bj, At, Bt) do { __builtin_amdgcn_s_setprio(1); _Pragma("unroll") for (int m = 0; m < 4; ++m) _Pragma("unroll") for (int n = 0; n < 2; ++n) _Pragma("unroll") for (int k = 0; k < 2; ++k) \
;         acc[ai][bj][m][n] = __builtin_amdgcn_mfma_f32_16x16x32_bf16(Bt[n][k], At[m][k], acc[ai][bj][m][n], 0, 0, 0); __builtin_amdgcn_s_setprio(0); } while (0)
; #define PG8_WAIT_V(n) asm volatile("s_waitcnt vmcnt(" #n ")" ::: "memory")
; #define PG8_WAIT_L(n) asm volatile("s_waitcnt lgkmcnt(" #n ")" ::: "memory")
; #define PG8_BAR __builtin_amdgcn_s_barrier()
; #define PG8_SCHED __builtin_amdgcn_sched_barrier(0)
; template <class Epi, class Sched>
; __device__ __forceinline__ void gemm_phase(LAS unsigned char* lds, const Gemm g, const Sched& S, const Epi& E) {
;     ...
;             PG8_LDB(B0, 0, 0); PG8_SCHED; PG8_LDA(At, 0, 0); PG8_STAGE(PG8_SA(1, 1), a1 + hstep, voffA);
;             PG8_WAIT_L(8); PG8_BAR; PG8_WAIT_L(0); PG8_MMA(0, 0, At, B0); PG8_BAR; PG8_SCHED;
;             PG8_LDB(B1, 0, 1); PG8_STAGE(PG8_SB(0, 0), b2, voffB);
;             PG8_BAR; PG8_WAIT_L(0); PG8_MMA(0, 1, At, B1); PG8_BAR;
;             PG8_LDA(At, 0, 1); PG8_STAGE(PG8_SA(0, 0), a2, voffA);
;             PG8_BAR; PG8_WAIT_L(0); PG8_MMA(1, 0, At, B0); PG8_BAR; PG8_SCHED;
;             PG8_STAGE(PG8_SB(0, 1), b2 + hstep, voffB);
;             PG8_WAIT_V(6); PG8_BAR; PG8_MMA(1, 1, At, B1); PG8_BAR;
.LBB0_1279:
	s_nop 0
	v_add_u32_e32 v140, s47, v143
	ds_read_b128 v[146:149], v140
	ds_read_b128 v[150:153], v140 offset:1024
	ds_read_b128 v[154:157], v140 offset:2048
	ds_read_b128 v[158:161], v140 offset:3072
	s_add_u32 s22, s20, 0xfff80080
	s_addc_u32 s23, s21, -1
	s_cmp_eq_u32 s43, 28
	s_cselect_b32 s25, s3, s23
	s_cselect_b32 s24, s11, s22
	s_cselect_b32 s23, s9, s42
	s_cselect_b32 s22, s40, s41
	ds_read_b128 v[162:165], v145
	ds_read_b128 v[166:169], v145 offset:1024
	ds_read_b128 v[170:173], v145 offset:2048
	ds_read_b128 v[174:177], v145 offset:3072
	ds_read_b128 v[178:181], v145 offset:4096
	ds_read_b128 v[182:185], v145 offset:5120
	ds_read_b128 v[186:189], v145 offset:6144
	ds_read_b128 v[190:193], v145 offset:7168
	s_waitcnt lgkmcnt(8)
	s_barrier
	s_waitcnt lgkmcnt(0)
	v_mfma_f32_16x16x32_bf16 v[126:129], v[146:149], v[162:165], v[126:129]
	v_mfma_f32_16x16x32_bf16 v[122:125], v[154:157], v[162:165], v[122:125]
	v_mfma_f32_16x16x32_bf16 v[110:113], v[146:149], v[170:173], v[110:113]
	v_mfma_f32_16x16x32_bf16 v[106:109], v[154:157], v[170:173], v[106:109]
	s_add_i32 m0, s17, 0xc000
	v_mfma_f32_16x16x32_bf16 v[94:97], v[146:149], v[178:181], v[94:97]
	global_load_lds_dwordx4 v136, s[20:21]
	v_mfma_f32_16x16x32_bf16 v[90:93], v[154:157], v[178:181], v[90:93]
	v_mfma_f32_16x16x32_bf16 v[78:81], v[146:149], v[186:189], v[78:81]
	v_mfma_f32_16x16x32_bf16 v[74:77], v[154:157], v[186:189], v[74:77]
	v_mfma_f32_16x16x32_bf16 v[126:129], v[150:153], v[166:169], v[126:129]
	v_mfma_f32_16x16x32_bf16 v[122:125], v[158:161], v[166:169], v[122:125]
	s_add_i32 m0, s17, 0xe000
	v_mfma_f32_16x16x32_bf16 v[110:113], v[150:153], v[174:177], v[110:113]
	global_load_lds_dwordx4 v138, s[20:21]
	v_mfma_f32_16x16x32_bf16 v[106:109], v[158:161], v[174:177], v[106:109]
	v_mfma_f32_16x16x32_bf16 v[94:97], v[150:153], v[182:185], v[94:97]
	v_mfma_f32_16x16x32_bf16 v[90:93], v[158:161], v[182:185], v[90:93]
	v_mfma_f32_16x16x32_bf16 v[78:81], v[150:153], v[190:193], v[78:81]
	v_mfma_f32_16x16x32_bf16 v[74:77], v[158:161], v[190:193], v[74:77]
	s_barrier
	s_add_i32 s46, 0, 0x14000
	v_add_u32_e32 v140, s46, v143
	s_add_i32 s44, s47, s30
	ds_read_b128 v[194:197], v140
	ds_read_b128 v[198:201], v140 offset:1024
	ds_read_b128 v[202:205], v140 offset:2048
	ds_read_b128 v[206:209], v140 offset:3072
	s_mov_b32 m0, s44
	s_nop 0
	global_load_lds_dwordx4 v0, s[22:23]
	s_add_i32 m0, s44, 0x2000
	s_nop 0
	global_load_lds_dwordx4 v130, s[22:23]
	s_barrier
	s_waitcnt lgkmcnt(0)
	v_mfma_f32_16x16x32_bf16 v[118:121], v[194:197], v[162:165], v[118:121]
	v_mfma_f32_16x16x32_bf16 v[114:117], v[202:205], v[162:165], v[114:117]
	v_mfma_f32_16x16x32_bf16 v[102:105], v[194:197], v[170:173], v[102:105]
	v_mfma_f32_16x16x32_bf16 v[98:101], v[202:205], v[170:173], v[98:101]
	v_mfma_f32_16x16x32_bf16 v[86:89], v[194:197], v[178:181], v[86:89]
	v_mfma_f32_16x16x32_bf16 v[82:85], v[202:205], v[178:181], v[82:85]
	v_mfma_f32_16x16x32_bf16 v[70:73], v[194:197], v[186:189], v[70:73]
	v_mfma_f32_16x16x32_bf16 v[66:69], v[202:205], v[186:189], v[66:69]
	v_mfma_f32_16x16x32_bf16 v[118:121], v[198:201], v[166:169], v[118:121]
	v_mfma_f32_16x16x32_bf16 v[114:117], v[206:209], v[166:169], v[114:117]
	v_mfma_f32_16x16x32_bf16 v[102:105], v[198:201], v[174:177], v[102:105]
	v_mfma_f32_16x16x32_bf16 v[98:101], v[206:209], v[174:177], v[98:101]
	v_mfma_f32_16x16x32_bf16 v[86:89], v[198:201], v[182:185], v[86:89]
	v_mfma_f32_16x16x32_bf16 v[82:85], v[206:209], v[182:185], v[82:85]
	v_mfma_f32_16x16x32_bf16 v[70:73], v[198:201], v[190:193], v[70:73]
	v_mfma_f32_16x16x32_bf16 v[66:69], v[206:209], v[190:193], v[66:69]
	s_add_u32 s48, s24, 0x80
	s_addc_u32 s49, s25, 0
	s_barrier
	ds_read_b128 v[162:165], v145 offset:16384
	ds_read_b128 v[166:169], v145 offset:17408
	ds_read_b128 v[170:173], v145 offset:18432
	ds_read_b128 v[174:177], v145 offset:19456
	ds_read_b128 v[178:181], v145 offset:20480
	ds_read_b128 v[182:185], v145 offset:21504
	ds_read_b128 v[186:189], v145 offset:22528
	ds_read_b128 v[190:193], v145 offset:23552
	s_barrier
	s_waitcnt lgkmcnt(0)
	v_mfma_f32_16x16x32_bf16 v[62:65], v[146:149], v[162:165], v[62:65]
	v_mfma_f32_16x16x32_bf16 v[58:61], v[154:157], v[162:165], v[58:61]
	v_mfma_f32_16x16x32_bf16 v[46:49], v[146:149], v[170:173], v[46:49]
	v_mfma_f32_16x16x32_bf16 v[42:45], v[154:157], v[170:173], v[42:45]
	s_mov_b32 m0, s17
	v_mfma_f32_16x16x32_bf16 v[30:33], v[146:149], v[178:181], v[30:33]
	global_load_lds_dwordx4 v134, s[24:25]
	v_mfma_f32_16x16x32_bf16 v[26:29], v[154:157], v[178:181], v[26:29]
	v_mfma_f32_16x16x32_bf16 v[14:17], v[146:149], v[186:189], v[14:17]
	v_mfma_f32_16x16x32_bf16 v[10:13], v[154:157], v[186:189], v[10:13]
	v_mfma_f32_16x16x32_bf16 v[62:65], v[150:153], v[166:169], v[62:65]
	v_mfma_f32_16x16x32_bf16 v[58:61], v[158:161], v[166:169], v[58:61]
	s_mov_b32 m0, s19
	v_mfma_f32_16x16x32_bf16 v[46:49], v[150:153], v[174:177], v[46:49]
	global_load_lds_dwordx4 v132, s[24:25]
	v_mfma_f32_16x16x32_bf16 v[42:45], v[158:161], v[174:177], v[42:45]
	v_mfma_f32_16x16x32_bf16 v[30:33], v[150:153], v[182:185], v[30:33]
	v_mfma_f32_16x16x32_bf16 v[26:29], v[158:161], v[182:185], v[26:29]
	v_mfma_f32_16x16x32_bf16 v[14:17], v[150:153], v[190:193], v[14:17]
	v_mfma_f32_16x16x32_bf16 v[10:13], v[158:161], v[190:193], v[10:13]
	s_barrier
	s_add_u32 s44, s22, 0x80000
	s_addc_u32 s45, s23, 0
	s_add_i32 s46, s46, s30
	s_mov_b32 m0, s46
	s_nop 0
	global_load_lds_dwordx4 v0, s[44:45]
	s_add_i32 m0, s46, 0x2000
	s_nop 0
	global_load_lds_dwordx4 v130, s[44:45]
	s_waitcnt vmcnt(6)
	s_barrier
; #define PG8_STAGE(bufoff, gbase, voff) do { _Pragma("unroll") for (int _i = 0; _i < 2; ++_i) \
;         __builtin_amdgcn_global_load_lds((const unsigned*)((const char*)(gbase) + (voff)[_i]), (LAS unsigned*)(lds + (bufoff) + ldsw + _i * 8192), 16, 0, 0); } while (0)
; #define PG8_LDA(dst, b, h) do { _Pragma("unroll") for (int m = 0; m < 4; ++m) _Pragma("unroll") for (int k = 0; k < 2; ++k) dst[m][k] = *(const LAS bf16x8*)(lds + PG8_SA(b, h) + aoff + m * 2048 + k * 1024); } while (0)
; #define PG8_LDB(dst, b, h) do { _Pragma("unroll") for (int n = 0; n < 2; ++n) _Pragma("unroll") for (int k = 0; k < 2; ++k) dst[n][k] = *(const LAS bf16x8*)(lds + PG8_SB(b, h) + boff + n * 2048 + k * 1024); } while (0)
; #define PG8_MMA(ai, bj, At, Bt) do { __builtin_amdgcn_s_setprio(1); _Pragma("unroll") for (int m = 0; m < 4; ++m) _Pragma("unroll") for (int n = 0; n < 2; ++n) _Pragma("unroll") for (int k = 0; k < 2; ++k) \
;         acc[ai][bj][m][n] = __builtin_amdgcn_mfma_f32_16x16x32_bf16(Bt[n][k], At[m][k], acc[ai][bj][m][n], 0, 0, 0); __builtin_amdgcn_s_setprio(0); } while (0)
; #define PG8_WAIT_V(n) asm volatile("s_waitcnt vmcnt(" #n ")" ::: "memory")
; #define PG8_WAIT_L(n) asm volatile("s_waitcnt lgkmcnt(" #n ")" ::: "memory")
; #define PG8_BAR __builtin_amdgcn_s_barrier()
; #define PG8_SCHED __builtin_amdgcn_sched_barrier(0)
; template <class Epi, class Sched>
; __device__ __forceinline__ void gemm_phase(LAS unsigned char* lds, const Gemm g, const Sched& S, const Epi& E) {
;     ...
;             PG8_WAIT_V(6); PG8_BAR; PG8_MMA(1, 1, At, B1); PG8_BAR;
;             PG8_LDB(B0, 1, 0); PG8_SCHED; PG8_LDA(At, 1, 0); PG8_STAGE(PG8_SA(0, 1), a2 + hstep, voffA);
;             PG8_WAIT_L(8); PG8_BAR; PG8_WAIT_L(0); PG8_MMA(0, 0, At, B0); PG8_BAR; PG8_SCHED;
;             PG8_LDB(B1, 1, 1); PG8_STAGE(PG8_SB(1, 0), b3, voffB);
;             PG8_BAR; PG8_WAIT_L(0); PG8_MMA(0, 1, At, B1); PG8_BAR;
;             PG8_LDA(At, 1, 1); PG8_STAGE(PG8_SA(1, 0), a3, voffA);
;             PG8_BAR; PG8_WAIT_L(0); PG8_MMA(1, 0, At, B0); PG8_BAR; PG8_SCHED;
	v_mfma_f32_16x16x32_bf16 v[54:57], v[194:197], v[162:165], v[54:57]
	v_mfma_f32_16x16x32_bf16 v[50:53], v[202:205], v[162:165], v[50:53]
	v_mfma_f32_16x16x32_bf16 v[38:41], v[194:197], v[170:173], v[38:41]
	v_mfma_f32_16x16x32_bf16 v[34:37], v[202:205], v[170:173], v[34:37]
	v_mfma_f32_16x16x32_bf16 v[22:25], v[194:197], v[178:181], v[22:25]
	v_mfma_f32_16x16x32_bf16 v[18:21], v[202:205], v[178:181], v[18:21]
	v_mfma_f32_16x16x32_bf16 v[6:9], v[194:197], v[186:189], v[6:9]
	v_mfma_f32_16x16x32_bf16 v[2:5], v[202:205], v[186:189], v[2:5]
	v_mfma_f32_16x16x32_bf16 v[54:57], v[198:201], v[166:169], v[54:57]
	v_mfma_f32_16x16x32_bf16 v[50:53], v[206:209], v[166:169], v[50:53]
	v_mfma_f32_16x16x32_bf16 v[38:41], v[198:201], v[174:177], v[38:41]
	v_mfma_f32_16x16x32_bf16 v[34:37], v[206:209], v[174:177], v[34:37]
	v_mfma_f32_16x16x32_bf16 v[22:25], v[198:201], v[182:185], v[22:25]
	v_mfma_f32_16x16x32_bf16 v[18:21], v[206:209], v[182:185], v[18:21]
	v_mfma_f32_16x16x32_bf16 v[6:9], v[198:201], v[190:193], v[6:9]
	v_mfma_f32_16x16x32_bf16 v[2:5], v[206:209], v[190:193], v[2:5]
	s_add_i32 s44, 0, 0x18000
	v_add_u32_e32 v158, s44, v143
	s_barrier
	ds_read_b128 v[146:149], v158
	ds_read_b128 v[150:153], v158 offset:1024
	ds_read_b128 v[154:157], v158 offset:2048
	ds_read_b128 v[158:161], v158 offset:3072
	s_add_u32 s24, s24, 0x80000
	s_addc_u32 s25, s25, 0
	ds_read_b128 v[162:165], v145 offset:32768
	ds_read_b128 v[166:169], v145 offset:33792
	ds_read_b128 v[170:173], v145 offset:34816
	ds_read_b128 v[174:177], v145 offset:35840
	ds_read_b128 v[178:181], v145 offset:36864
	ds_read_b128 v[182:185], v145 offset:37888
	ds_read_b128 v[186:189], v145 offset:38912
	ds_read_b128 v[190:193], v145 offset:39936
	s_waitcnt lgkmcnt(8)
	s_barrier
	s_waitcnt lgkmcnt(0)
	v_mfma_f32_16x16x32_bf16 v[126:129], v[146:149], v[162:165], v[126:129]
	v_mfma_f32_16x16x32_bf16 v[122:125], v[154:157], v[162:165], v[122:125]
	v_mfma_f32_16x16x32_bf16 v[110:113], v[146:149], v[170:173], v[110:113]
	v_mfma_f32_16x16x32_bf16 v[106:109], v[154:157], v[170:173], v[106:109]
	s_mov_b32 m0, s35
	v_mfma_f32_16x16x32_bf16 v[94:97], v[146:149], v[178:181], v[94:97]
	global_load_lds_dwordx4 v134, s[24:25]
	v_mfma_f32_16x16x32_bf16 v[90:93], v[154:157], v[178:181], v[90:93]
	v_mfma_f32_16x16x32_bf16 v[78:81], v[146:149], v[186:189], v[78:81]
	v_mfma_f32_16x16x32_bf16 v[74:77], v[154:157], v[186:189], v[74:77]
	v_mfma_f32_16x16x32_bf16 v[126:129], v[150:153], v[166:169], v[126:129]
	v_mfma_f32_16x16x32_bf16 v[122:125], v[158:161], v[166:169], v[122:125]
	s_mov_b32 m0, s36
	v_mfma_f32_16x16x32_bf16 v[110:113], v[150:153], v[174:177], v[110:113]
	global_load_lds_dwordx4 v132, s[24:25]
	v_mfma_f32_16x16x32_bf16 v[106:109], v[158:161], v[174:177], v[106:109]
	v_mfma_f32_16x16x32_bf16 v[94:97], v[150:153], v[182:185], v[94:97]
	v_mfma_f32_16x16x32_bf16 v[90:93], v[158:161], v[182:185], v[90:93]
	v_mfma_f32_16x16x32_bf16 v[78:81], v[150:153], v[190:193], v[78:81]
	v_mfma_f32_16x16x32_bf16 v[74:77], v[158:161], v[190:193], v[74:77]
	s_barrier
	s_add_i32 s24, 0, 0x1c000
	s_add_i32 s25, s44, s30
	v_add_u32_e32 v206, s24, v143
	s_add_u32 s44, s22, 0x80
	s_addc_u32 s45, s23, 0
	s_mov_b32 m0, s25
	ds_read_b128 v[194:197], v206
	ds_read_b128 v[198:201], v206 offset:1024
	ds_read_b128 v[202:205], v206 offset:2048
	ds_read_b128 v[206:209], v206 offset:3072
	global_load_lds_dwordx4 v0, s[44:45]
	s_add_i32 m0, s25, 0x2000
	s_nop 0
	global_load_lds_dwordx4 v130, s[44:45]
	s_barrier
	s_waitcnt lgkmcnt(0)
	v_mfma_f32_16x16x32_bf16 v[118:121], v[194:197], v[162:165], v[118:121]
	v_mfma_f32_16x16x32_bf16 v[114:117], v[202:205], v[162:165], v[114:117]
	v_mfma_f32_16x16x32_bf16 v[102:105], v[194:197], v[170:173], v[102:105]
	v_mfma_f32_16x16x32_bf16 v[98:101], v[202:205], v[170:173], v[98:101]
	v_mfma_f32_16x16x32_bf16 v[86:89], v[194:197], v[178:181], v[86:89]
	v_mfma_f32_16x16x32_bf16 v[82:85], v[202:205], v[178:181], v[82:85]
	v_mfma_f32_16x16x32_bf16 v[70:73], v[194:197], v[186:189], v[70:73]
	v_mfma_f32_16x16x32_bf16 v[66:69], v[202:205], v[186:189], v[66:69]
	v_mfma_f32_16x16x32_bf16 v[118:121], v[198:201], v[166:169], v[118:121]
	v_mfma_f32_16x16x32_bf16 v[114:117], v[206:209], v[166:169], v[114:117]
	v_mfma_f32_16x16x32_bf16 v[102:105], v[198:201], v[174:177], v[102:105]
	v_mfma_f32_16x16x32_bf16 v[98:101], v[206:209], v[174:177], v[98:101]
	v_mfma_f32_16x16x32_bf16 v[86:89], v[198:201], v[182:185], v[86:89]
	v_mfma_f32_16x16x32_bf16 v[82:85], v[206:209], v[182:185], v[82:85]
	v_mfma_f32_16x16x32_bf16 v[70:73], v[198:201], v[190:193], v[70:73]
	v_mfma_f32_16x16x32_bf16 v[66:69], v[206:209], v[190:193], v[66:69]
	s_barrier
	ds_read_b128 v[162:165], v145 offset:49152
	ds_read_b128 v[166:169], v145 offset:50176
	ds_read_b128 v[170:173], v145 offset:51200
	ds_read_b128 v[174:177], v145 offset:52224
	ds_read_b128 v[178:181], v145 offset:53248
	ds_read_b128 v[182:185], v145 offset:54272
	ds_read_b128 v[186:189], v145 offset:55296
	ds_read_b128 v[190:193], v145 offset:56320
	s_barrier
	s_waitcnt lgkmcnt(0)
	v_mfma_f32_16x16x32_bf16 v[62:65], v[146:149], v[162:165], v[62:65]
	v_mfma_f32_16x16x32_bf16 v[58:61], v[154:157], v[162:165], v[58:61]
	v_mfma_f32_16x16x32_bf16 v[46:49], v[146:149], v[170:173], v[46:49]
	v_mfma_f32_16x16x32_bf16 v[42:45], v[154:157], v[170:173], v[42:45]
	s_mov_b32 m0, s37
	v_mfma_f32_16x16x32_bf16 v[30:33], v[146:149], v[178:181], v[30:33]
	global_load_lds_dwordx4 v134, s[48:49]
	v_mfma_f32_16x16x32_bf16 v[26:29], v[154:157], v[178:181], v[26:29]
	v_mfma_f32_16x16x32_bf16 v[14:17], v[146:149], v[186:189], v[14:17]
	v_mfma_f32_16x16x32_bf16 v[10:13], v[154:157], v[186:189], v[10:13]
	v_mfma_f32_16x16x32_bf16 v[62:65], v[150:153], v[166:169], v[62:65]
	v_mfma_f32_16x16x32_bf16 v[58:61], v[158:161], v[166:169], v[58:61]
	s_mov_b32 m0, s38
	v_mfma_f32_16x16x32_bf16 v[46:49], v[150:153], v[174:177], v[46:49]
	global_load_lds_dwordx4 v132, s[48:49]
	v_mfma_f32_16x16x32_bf16 v[42:45], v[158:161], v[174:177], v[42:45]
	v_mfma_f32_16x16x32_bf16 v[30:33], v[150:153], v[182:185], v[30:33]
	v_mfma_f32_16x16x32_bf16 v[26:29], v[158:161], v[182:185], v[26:29]
	v_mfma_f32_16x16x32_bf16 v[14:17], v[150:153], v[190:193], v[14:17]
	v_mfma_f32_16x16x32_bf16 v[10:13], v[158:161], v[190:193], v[10:13]
	s_barrier
; __device__ __forceinline__ unsigned cvt_pk_bf16(float lo, float hi) { f32x2_t v = {lo, hi}; bf16x2_t b = __builtin_convertvector(v, bf16x2_t); return __builtin_bit_cast(unsigned, b); }
; #define PG8_STAGE(bufoff, gbase, voff) do { _Pragma("unroll") for (int _i = 0; _i < 2; ++_i) \
;         __builtin_amdgcn_global_load_lds((const unsigned*)((const char*)(gbase) + (voff)[_i]), (LAS unsigned*)(lds + (bufoff) + ldsw + _i * 8192), 16, 0, 0); } while (0)
; #define PG8_MMA(ai, bj, At, Bt) do { __builtin_amdgcn_s_setprio(1); _Pragma("unroll") for (int m = 0; m < 4; ++m) _Pragma("unroll") for (int n = 0; n < 2; ++n) _Pragma("unroll") for (int k = 0; k < 2; ++k) \
;         acc[ai][bj][m][n] = __builtin_amdgcn_mfma_f32_16x16x32_bf16(Bt[n][k], At[m][k], acc[ai][bj][m][n], 0, 0, 0); __builtin_amdgcn_s_setprio(0); } while (0)
; #define PG8_WAIT_V(n) asm volatile("s_waitcnt vmcnt(" #n ")" ::: "memory")
; template <class Epi, class Sched>
; __device__ __forceinline__ void gemm_phase(LAS unsigned char* lds, const Gemm g, const Sched& S, const Epi& E) {
;     ...
;             PG8_STAGE(PG8_SB(1, 1), b3 + hstep, voffB);
;             PG8_WAIT_V(6); PG8_BAR; PG8_MMA(1, 1, At, B1); PG8_BAR;
;     __device__ __forceinline__ void operator()(const f32x4 (&acc)[2][2][4][2], const pg8::Unit& u, int wr, int wc, int fr, int fq) const {
;         const int row0 = u.pm * 256 + wr * 64 + fr; const int col0 = u.pn * 256 + wc * 32 + 8 * fq;
; #pragma unroll
;         for (int ai = 0; ai < 2; ++ai)
; #pragma unroll
;             for (int m = 0; m < 4; ++m) { const int row = row0 + ai * 128 + m * 16; bf16_t* rowp = O + (size_t)row * ldc + col0;
; #pragma unroll
;                 for (int bj = 0; bj < 2; ++bj) { f32x4 v0 = acc[ai][bj][m][0], v1 = acc[ai][bj][m][1];
;                     if (ACT == 1) {
; #pragma unroll
;                         for (int j = 0; j < 4; ++j) { float a = fmaxf(v0[j], 0.f), b = fmaxf(v1[j], 0.f); v0[j] = a * a; v1[j] = b * b; } }
;                     if (ACT == 0) { if (u.pn == (C_G / 256) && bj == 0 && wc == 0 && fq < 2) { float* gp = gate + (size_t)row * 16 + 8 * fq; *(f32x4*)gp = v0; *(f32x4*)(gp + 4) = v1; } }
;                     u32x4 w; w.x = cvt_pk_bf16(v0[0], v0[1]); w.y = cvt_pk_bf16(v0[2], v0[3]); w.z = cvt_pk_bf16(v1[0], v1[1]); w.w = cvt_pk_bf16(v1[2], v1[3]);
;                     *(u32x4*)(rowp + bj * 128) = w; } }
	s_add_u32 s22, s22, 0x80080
	s_addc_u32 s23, s23, 0
	s_add_i32 s24, s24, s30
	s_mov_b32 m0, s24
	s_nop 0
	global_load_lds_dwordx4 v0, s[22:23]
	s_add_i32 m0, s24, 0x2000
	s_nop 0
	global_load_lds_dwordx4 v130, s[22:23]
	s_waitcnt vmcnt(6)
	s_barrier
	v_mfma_f32_16x16x32_bf16 v[54:57], v[194:197], v[162:165], v[54:57]
	v_mfma_f32_16x16x32_bf16 v[50:53], v[202:205], v[162:165], v[50:53]
	v_mfma_f32_16x16x32_bf16 v[38:41], v[194:197], v[170:173], v[38:41]
	v_mfma_f32_16x16x32_bf16 v[34:37], v[202:205], v[170:173], v[34:37]
	v_mfma_f32_16x16x32_bf16 v[22:25], v[194:197], v[178:181], v[22:25]
	v_mfma_f32_16x16x32_bf16 v[18:21], v[202:205], v[178:181], v[18:21]
	v_mfma_f32_16x16x32_bf16 v[6:9], v[194:197], v[186:189], v[6:9]
	v_mfma_f32_16x16x32_bf16 v[2:5], v[202:205], v[186:189], v[2:5]
	v_mfma_f32_16x16x32_bf16 v[54:57], v[198:201], v[166:169], v[54:57]
	v_mfma_f32_16x16x32_bf16 v[50:53], v[206:209], v[166:169], v[50:53]
	v_mfma_f32_16x16x32_bf16 v[38:41], v[198:201], v[174:177], v[38:41]
	v_mfma_f32_16x16x32_bf16 v[34:37], v[206:209], v[174:177], v[34:37]
	v_mfma_f32_16x16x32_bf16 v[22:25], v[198:201], v[182:185], v[22:25]
	v_mfma_f32_16x16x32_bf16 v[18:21], v[206:209], v[182:185], v[18:21]
	v_mfma_f32_16x16x32_bf16 v[6:9], v[198:201], v[190:193], v[6:9]
	v_mfma_f32_16x16x32_bf16 v[2:5], v[206:209], v[190:193], v[2:5]
	s_add_i32 s43, s43, 2
	s_add_u32 s20, s20, 0x100
	s_addc_u32 s21, s21, 0
	s_add_u32 s41, s41, 0x100
	s_addc_u32 s42, s42, 0
	s_cmp_gt_u32 s43, 29
	s_barrier
	s_cbranch_scc0 .LBB0_1279
	v_lshl_add_u32 v146, s18, 8, v142
	v_lshl_or_b32 v140, s16, 8, v144
	v_ashrrev_i32_e32 v147, 31, v146
	v_ashrrev_i32_e32 v141, 31, v140
	v_lshlrev_b64 v[148:149], 14, v[146:147]
	v_max_f32_e32 v122, v122, v122
	v_max_f32_e32 v123, v123, v123
	v_lshl_add_u64 v[148:149], s[58:59], 0, v[148:149]
	v_lshlrev_b64 v[150:151], 1, v[140:141]
	v_max_f32_e32 v122, 0, v122
	v_max_f32_e32 v123, 0, v123
	v_lshl_add_u64 v[140:141], v[148:149], 0, v[150:151]
	v_pk_mul_f32 v[148:149], v[122:123], v[122:123]
	v_max_f32_e32 v123, v124, v124
	v_max_f32_e32 v126, v126, v126
	v_max_f32_e32 v127, v127, v127
	v_max_f32_e32 v122, v128, v128
	v_max_f32_e32 v124, 0, v123
	v_max_f32_e32 v123, v129, v129
	v_max_f32_e32 v125, v125, v125
	v_max_f32_e32 v126, 0, v126
	v_max_f32_e32 v127, 0, v127
	v_max_f32_e32 v122, 0, v122
	v_max_f32_e32 v123, 0, v123
	v_max_f32_e32 v125, 0, v125
	v_pk_mul_f32 v[126:127], v[126:127], v[126:127]
	v_pk_mul_f32 v[128:129], v[122:123], v[122:123]
	v_pk_mul_f32 v[152:153], v[124:125], v[124:125]
	v_max_f32_e32 v114, v114, v114
	v_max_f32_e32 v115, v115, v115
	v_cvt_pk_bf16_f32 v122, v126, v127
	v_cvt_pk_bf16_f32 v123, v128, v129
	v_cvt_pk_bf16_f32 v124, v148, v149
	v_cvt_pk_bf16_f32 v125, v152, v153
	v_max_f32_e32 v114, 0, v114
	v_max_f32_e32 v115, 0, v115
	global_store_dwordx4 v[140:141], v[122:125], off
	v_max_f32_e32 v118, v118, v118
	v_max_f32_e32 v119, v119, v119
	v_pk_mul_f32 v[122:123], v[114:115], v[114:115]
	v_max_f32_e32 v115, v116, v116
	v_max_f32_e32 v114, v120, v120
	v_max_f32_e32 v116, 0, v115
	v_max_f32_e32 v115, v121, v121
	v_max_f32_e32 v117, v117, v117
	v_max_f32_e32 v118, 0, v118
	v_max_f32_e32 v119, 0, v119
	v_max_f32_e32 v114, 0, v114
	v_max_f32_e32 v115, 0, v115
	v_max_f32_e32 v117, 0, v117
	v_pk_mul_f32 v[118:119], v[118:119], v[118:119]
	v_pk_mul_f32 v[120:121], v[114:115], v[114:115]
	v_pk_mul_f32 v[124:125], v[116:117], v[116:117]
	v_max_f32_e32 v106, v106, v106
	v_max_f32_e32 v107, v107, v107
	v_cvt_pk_bf16_f32 v114, v118, v119
	v_cvt_pk_bf16_f32 v115, v120, v121
	v_cvt_pk_bf16_f32 v116, v122, v123
	v_cvt_pk_bf16_f32 v117, v124, v125
	v_max_f32_e32 v106, 0, v106
	v_max_f32_e32 v107, 0, v107
	global_store_dwordx4 v[140:141], v[114:117], off offset:256
	v_max_f32_e32 v110, v110, v110
	v_max_f32_e32 v111, v111, v111
	v_or_b32_e32 v114, 16, v146
	v_pk_mul_f32 v[116:117], v[106:107], v[106:107]
	v_max_f32_e32 v107, v108, v108
	v_ashrrev_i32_e32 v115, 31, v114
	v_max_f32_e32 v106, v112, v112
	v_max_f32_e32 v108, 0, v107
	v_max_f32_e32 v107, v113, v113
	v_max_f32_e32 v109, v109, v109
	v_lshlrev_b64 v[114:115], 14, v[114:115]
	v_max_f32_e32 v110, 0, v110
	v_max_f32_e32 v111, 0, v111
	v_max_f32_e32 v106, 0, v106
	v_max_f32_e32 v107, 0, v107
	v_max_f32_e32 v109, 0, v109
	v_lshl_add_u64 v[114:115], s[58:59], 0, v[114:115]
	v_pk_mul_f32 v[110:111], v[110:111], v[110:111]
	v_pk_mul_f32 v[112:113], v[106:107], v[106:107]
	v_pk_mul_f32 v[118:119], v[108:109], v[108:109]
	v_max_f32_e32 v98, v98, v98
	v_max_f32_e32 v99, v99, v99
	v_lshl_add_u64 v[114:115], v[114:115], 0, v[150:151]
	v_cvt_pk_bf16_f32 v106, v110, v111
	v_cvt_pk_bf16_f32 v107, v112, v113
	v_cvt_pk_bf16_f32 v108, v116, v117
	v_cvt_pk_bf16_f32 v109, v118, v119
	v_max_f32_e32 v98, 0, v98
	v_max_f32_e32 v99, 0, v99
	global_store_dwordx4 v[114:115], v[106:109], off
	v_max_f32_e32 v102, v102, v102
	v_max_f32_e32 v103, v103, v103
	v_pk_mul_f32 v[106:107], v[98:99], v[98:99]
	v_max_f32_e32 v99, v100, v100
	v_max_f32_e32 v98, v104, v104
	v_max_f32_e32 v100, 0, v99
	v_max_f32_e32 v99, v105, v105
	v_max_f32_e32 v101, v101, v101
	v_max_f32_e32 v102, 0, v102
	v_max_f32_e32 v103, 0, v103
	v_max_f32_e32 v98, 0, v98
	v_max_f32_e32 v99, 0, v99
	v_max_f32_e32 v101, 0, v101
	v_pk_mul_f32 v[102:103], v[102:103], v[102:103]
	v_pk_mul_f32 v[104:105], v[98:99], v[98:99]
	v_pk_mul_f32 v[108:109], v[100:101], v[100:101]
	v_max_f32_e32 v90, v90, v90
	v_max_f32_e32 v91, v91, v91
	v_cvt_pk_bf16_f32 v98, v102, v103
	v_cvt_pk_bf16_f32 v99, v104, v105
	v_cvt_pk_bf16_f32 v100, v106, v107
	v_cvt_pk_bf16_f32 v101, v108, v109
	v_max_f32_e32 v90, 0, v90
	v_max_f32_e32 v91, 0, v91
; __device__ __forceinline__ unsigned cvt_pk_bf16(float lo, float hi) { f32x2_t v = {lo, hi}; bf16x2_t b = __builtin_convertvector(v, bf16x2_t); return __builtin_bit_cast(unsigned, b); }
;     __device__ __forceinline__ void operator()(const f32x4 (&acc)[2][2][4][2], const pg8::Unit& u, int wr, int wc, int fr, int fq) const {
;     ...
;             for (int m = 0; m < 4; ++m) { const int row = row0 + ai * 128 + m * 16; bf16_t* rowp = O + (size_t)row * ldc + col0;
; #pragma unroll
;                 for (int bj = 0; bj < 2; ++bj) { f32x4 v0 = acc[ai][bj][m][0], v1 = acc[ai][bj][m][1];
;                     if (ACT == 1) {
; #pragma unroll
;                         for (int j = 0; j < 4; ++j) { float a = fmaxf(v0[j], 0.f), b = fmaxf(v1[j], 0.f); v0[j] = a * a; v1[j] = b * b; } }
;                     if (ACT == 0) { if (u.pn == (C_G / 256) && bj == 0 && wc == 0 && fq < 2) { float* gp = gate + (size_t)row * 16 + 8 * fq; *(f32x4*)gp = v0; *(f32x4*)(gp + 4) = v1; } }
;                     u32x4 w; w.x = cvt_pk_bf16(v0[0], v0[1]); w.y = cvt_pk_bf16(v0[2], v0[3]); w.z = cvt_pk_bf16(v1[0], v1[1]); w.w = cvt_pk_bf16(v1[2], v1[3]);
;                     *(u32x4*)(rowp + bj * 128) = w; } }
	global_store_dwordx4 v[114:115], v[98:101], off offset:256
	v_max_f32_e32 v94, v94, v94
	v_max_f32_e32 v95, v95, v95
	v_or_b32_e32 v98, 32, v146
	v_pk_mul_f32 v[100:101], v[90:91], v[90:91]
	v_max_f32_e32 v91, v92, v92
	v_ashrrev_i32_e32 v99, 31, v98
	v_max_f32_e32 v90, v96, v96
	v_max_f32_e32 v92, 0, v91
	v_max_f32_e32 v91, v97, v97
	v_max_f32_e32 v93, v93, v93
	v_lshlrev_b64 v[98:99], 14, v[98:99]
	v_max_f32_e32 v94, 0, v94
	v_max_f32_e32 v95, 0, v95
	v_max_f32_e32 v90, 0, v90
	v_max_f32_e32 v91, 0, v91
	v_max_f32_e32 v93, 0, v93
	v_lshl_add_u64 v[98:99], s[58:59], 0, v[98:99]
	v_pk_mul_f32 v[94:95], v[94:95], v[94:95]
	v_pk_mul_f32 v[96:97], v[90:91], v[90:91]
	v_pk_mul_f32 v[102:103], v[92:93], v[92:93]
	v_max_f32_e32 v82, v82, v82
	v_max_f32_e32 v83, v83, v83
	v_lshl_add_u64 v[98:99], v[98:99], 0, v[150:151]
	v_cvt_pk_bf16_f32 v90, v94, v95
	v_cvt_pk_bf16_f32 v91, v96, v97
	v_cvt_pk_bf16_f32 v92, v100, v101
	v_cvt_pk_bf16_f32 v93, v102, v103
	v_max_f32_e32 v82, 0, v82
	v_max_f32_e32 v83, 0, v83
	global_store_dwordx4 v[98:99], v[90:93], off
	v_max_f32_e32 v86, v86, v86
	v_max_f32_e32 v87, v87, v87
	v_pk_mul_f32 v[90:91], v[82:83], v[82:83]
	v_max_f32_e32 v83, v84, v84
	v_max_f32_e32 v82, v88, v88
	v_max_f32_e32 v84, 0, v83
	v_max_f32_e32 v83, v89, v89
	v_max_f32_e32 v85, v85, v85
	v_max_f32_e32 v86, 0, v86
	v_max_f32_e32 v87, 0, v87
	v_max_f32_e32 v82, 0, v82
	v_max_f32_e32 v83, 0, v83
	v_max_f32_e32 v85, 0, v85
	v_pk_mul_f32 v[86:87], v[86:87], v[86:87]
	v_pk_mul_f32 v[88:89], v[82:83], v[82:83]
	v_pk_mul_f32 v[92:93], v[84:85], v[84:85]
	v_max_f32_e32 v74, v74, v74
	v_max_f32_e32 v75, v75, v75
	v_cvt_pk_bf16_f32 v82, v86, v87
	v_cvt_pk_bf16_f32 v83, v88, v89
	v_cvt_pk_bf16_f32 v84, v90, v91
	v_cvt_pk_bf16_f32 v85, v92, v93
	v_max_f32_e32 v74, 0, v74
	v_max_f32_e32 v75, 0, v75
	global_store_dwordx4 v[98:99], v[82:85], off offset:256
	v_max_f32_e32 v78, v78, v78
	v_max_f32_e32 v79, v79, v79
	v_or_b32_e32 v82, 48, v146
	v_pk_mul_f32 v[84:85], v[74:75], v[74:75]
	v_max_f32_e32 v75, v76, v76
	v_ashrrev_i32_e32 v83, 31, v82
	v_max_f32_e32 v74, v80, v80
	v_max_f32_e32 v76, 0, v75
	v_max_f32_e32 v75, v81, v81
	v_max_f32_e32 v77, v77, v77
	v_lshlrev_b64 v[82:83], 14, v[82:83]
	v_max_f32_e32 v78, 0, v78
	v_max_f32_e32 v79, 0, v79
	v_max_f32_e32 v74, 0, v74
	v_max_f32_e32 v75, 0, v75
	v_max_f32_e32 v77, 0, v77
	v_lshl_add_u64 v[82:83], s[58:59], 0, v[82:83]
	v_pk_mul_f32 v[78:79], v[78:79], v[78:79]
	v_pk_mul_f32 v[80:81], v[74:75], v[74:75]
	v_pk_mul_f32 v[86:87], v[76:77], v[76:77]
	v_max_f32_e32 v66, v66, v66
	v_max_f32_e32 v67, v67, v67
	v_lshl_add_u64 v[82:83], v[82:83], 0, v[150:151]
	v_cvt_pk_bf16_f32 v74, v78, v79
	v_cvt_pk_bf16_f32 v75, v80, v81
	v_cvt_pk_bf16_f32 v76, v84, v85
	v_cvt_pk_bf16_f32 v77, v86, v87
	v_max_f32_e32 v66, 0, v66
	v_max_f32_e32 v67, 0, v67
	global_store_dwordx4 v[82:83], v[74:77], off
	v_max_f32_e32 v70, v70, v70
	v_max_f32_e32 v71, v71, v71
	v_pk_mul_f32 v[74:75], v[66:67], v[66:67]
	v_max_f32_e32 v67, v68, v68
	v_max_f32_e32 v66, v72, v72
	v_max_f32_e32 v68, 0, v67
	v_max_f32_e32 v67, v73, v73
	v_max_f32_e32 v69, v69, v69
	v_max_f32_e32 v70, 0, v70
	v_max_f32_e32 v71, 0, v71
	v_max_f32_e32 v66, 0, v66
	v_max_f32_e32 v67, 0, v67
	v_max_f32_e32 v69, 0, v69
	v_pk_mul_f32 v[70:71], v[70:71], v[70:71]
	v_pk_mul_f32 v[72:73], v[66:67], v[66:67]
	v_pk_mul_f32 v[76:77], v[68:69], v[68:69]
	v_max_f32_e32 v58, v58, v58
	v_max_f32_e32 v59, v59, v59
	v_cvt_pk_bf16_f32 v66, v70, v71
	v_cvt_pk_bf16_f32 v67, v72, v73
	v_cvt_pk_bf16_f32 v68, v74, v75
	v_cvt_pk_bf16_f32 v69, v76, v77
	v_max_f32_e32 v58, 0, v58
	v_max_f32_e32 v59, 0, v59
	global_store_dwordx4 v[82:83], v[66:69], off offset:256
	v_max_f32_e32 v62, v62, v62
	v_max_f32_e32 v63, v63, v63
	v_pk_mul_f32 v[68:69], v[58:59], v[58:59]
	v_max_f32_e32 v59, v60, v60
	v_max_f32_e32 v62, 0, v62
	v_max_f32_e32 v63, 0, v63
	v_max_f32_e32 v58, v64, v64
	v_max_f32_e32 v60, 0, v59
	v_max_f32_e32 v59, v65, v65
	v_max_f32_e32 v61, v61, v61
	v_pk_mul_f32 v[62:63], v[62:63], v[62:63]
	v_max_f32_e32 v58, 0, v58
	v_max_f32_e32 v59, 0, v59
	v_max_f32_e32 v61, 0, v61
	s_mov_b32 s3, 0x200000
	v_pk_mul_f32 v[64:65], v[58:59], v[58:59]
	v_pk_mul_f32 v[70:71], v[60:61], v[60:61]
	v_cvt_pk_bf16_f32 v58, v62, v63
	v_add_co_u32_e32 v62, vcc, s3, v140
	v_max_f32_e32 v50, v50, v50
	v_max_f32_e32 v51, v51, v51
	v_cvt_pk_bf16_f32 v59, v64, v65
	v_cvt_pk_bf16_f32 v60, v68, v69
	v_cvt_pk_bf16_f32 v61, v70, v71
	v_addc_co_u32_e32 v63, vcc, 0, v141, vcc
	v_max_f32_e32 v50, 0, v50
	v_max_f32_e32 v51, 0, v51
	global_store_dwordx4 v[62:63], v[58:61], off
	v_max_f32_e32 v54, v54, v54
	v_max_f32_e32 v55, v55, v55
	v_pk_mul_f32 v[58:59], v[50:51], v[50:51]
	v_max_f32_e32 v51, v52, v52
	v_max_f32_e32 v50, v56, v56
	v_max_f32_e32 v52, 0, v51
	v_max_f32_e32 v51, v57, v57
	v_max_f32_e32 v53, v53, v53
	v_max_f32_e32 v54, 0, v54
	v_max_f32_e32 v55, 0, v55
	v_max_f32_e32 v50, 0, v50
	v_max_f32_e32 v51, 0, v51
	v_max_f32_e32 v53, 0, v53
	s_mov_b64 s[20:21], 0x200000
	v_pk_mul_f32 v[54:55], v[54:55], v[54:55]
	v_pk_mul_f32 v[56:57], v[50:51], v[50:51]
	v_pk_mul_f32 v[60:61], v[52:53], v[52:53]
	v_max_f32_e32 v42, v42, v42
	v_max_f32_e32 v43, v43, v43
	v_lshl_add_u64 v[66:67], v[140:141], 0, s[20:21]
	v_cvt_pk_bf16_f32 v50, v54, v55
	v_cvt_pk_bf16_f32 v51, v56, v57
	v_cvt_pk_bf16_f32 v52, v58, v59
	v_cvt_pk_bf16_f32 v53, v60, v61
	v_max_f32_e32 v42, 0, v42
	v_max_f32_e32 v43, 0, v43
	global_store_dwordx4 v[66:67], v[50:53], off offset:256
; __device__ __forceinline__ unsigned cvt_pk_bf16(float lo, float hi) { f32x2_t v = {lo, hi}; bf16x2_t b = __builtin_convertvector(v, bf16x2_t); return __builtin_bit_cast(unsigned, b); }
; #define PG8_WAIT_V(n) asm volatile("s_waitcnt vmcnt(" #n ")" ::: "memory")
; #define PG8_BAR __builtin_amdgcn_s_barrier()
; template <class Epi, class Sched>
; __device__ __forceinline__ void gemm_phase(LAS unsigned char* lds, const Gemm g, const Sched& S, const Epi& E) {
;     ...
;         if (!has_next) break;
; #pragma unroll
;         for (int a = 0; a < 2; ++a)
; #pragma unroll
;             for (int b = 0; b < 2; ++b)
; #pragma unroll
;                 for (int m = 0; m < 4; ++m)
; #pragma unroll
;                     for (int n = 0; n < 2; ++n) acc[a][b][m][n] = (f32x4){0.f, 0.f, 0.f, 0.f};
;         cur = nxt; cA = nA; cB = nB; ++ui;
;     }
;     PG8_WAIT_V(0);
;     if (wr == 0) PG8_BAR;
;     PG8_BAR;
;     __device__ __forceinline__ void operator()(const f32x4 (&acc)[2][2][4][2], const pg8::Unit& u, int wr, int wc, int fr, int fq) const {
;     ...
;             for (int m = 0; m < 4; ++m) { const int row = row0 + ai * 128 + m * 16; bf16_t* rowp = O + (size_t)row * ldc + col0;
; #pragma unroll
;                 for (int bj = 0; bj < 2; ++bj) { f32x4 v0 = acc[ai][bj][m][0], v1 = acc[ai][bj][m][1];
;                     if (ACT == 1) {
; #pragma unroll
;                         for (int j = 0; j < 4; ++j) { float a = fmaxf(v0[j], 0.f), b = fmaxf(v1[j], 0.f); v0[j] = a * a; v1[j] = b * b; } }
;                     if (ACT == 0) { if (u.pn == (C_G / 256) && bj == 0 && wc == 0 && fq < 2) { float* gp = gate + (size_t)row * 16 + 8 * fq; *(f32x4*)gp = v0; *(f32x4*)(gp + 4) = v1; } }
;                     u32x4 w; w.x = cvt_pk_bf16(v0[0], v0[1]); w.y = cvt_pk_bf16(v0[2], v0[3]); w.z = cvt_pk_bf16(v1[0], v1[1]); w.w = cvt_pk_bf16(v1[2], v1[3]);
;                     *(u32x4*)(rowp + bj * 128) = w; } }
	v_max_f32_e32 v46, v46, v46
	v_max_f32_e32 v47, v47, v47
	v_pk_mul_f32 v[52:53], v[42:43], v[42:43]
	v_max_f32_e32 v43, v44, v44
	v_max_f32_e32 v46, 0, v46
	v_max_f32_e32 v47, 0, v47
	v_max_f32_e32 v42, v48, v48
	v_max_f32_e32 v44, 0, v43
	v_max_f32_e32 v43, v49, v49
	v_max_f32_e32 v45, v45, v45
	v_pk_mul_f32 v[46:47], v[46:47], v[46:47]
	v_max_f32_e32 v42, 0, v42
	v_max_f32_e32 v43, 0, v43
	v_max_f32_e32 v45, 0, v45
	s_mov_b32 s3, 0x240000
	v_pk_mul_f32 v[48:49], v[42:43], v[42:43]
	v_pk_mul_f32 v[54:55], v[44:45], v[44:45]
	v_cvt_pk_bf16_f32 v42, v46, v47
	v_add_co_u32_e32 v46, vcc, s3, v140
	v_max_f32_e32 v34, v34, v34
	v_max_f32_e32 v35, v35, v35
	v_cvt_pk_bf16_f32 v43, v48, v49
	v_cvt_pk_bf16_f32 v44, v52, v53
	v_cvt_pk_bf16_f32 v45, v54, v55
	v_addc_co_u32_e32 v47, vcc, 0, v141, vcc
	v_max_f32_e32 v34, 0, v34
	v_max_f32_e32 v35, 0, v35
	global_store_dwordx4 v[46:47], v[42:45], off
	v_max_f32_e32 v38, v38, v38
	v_max_f32_e32 v39, v39, v39
	v_pk_mul_f32 v[42:43], v[34:35], v[34:35]
	v_max_f32_e32 v35, v36, v36
	v_max_f32_e32 v34, v40, v40
	v_max_f32_e32 v36, 0, v35
	v_max_f32_e32 v35, v41, v41
	v_max_f32_e32 v37, v37, v37
	v_max_f32_e32 v38, 0, v38
	v_max_f32_e32 v39, 0, v39
	v_max_f32_e32 v34, 0, v34
	v_max_f32_e32 v35, 0, v35
	v_max_f32_e32 v37, 0, v37
	s_mov_b64 s[20:21], 0x240000
	v_pk_mul_f32 v[38:39], v[38:39], v[38:39]
	v_pk_mul_f32 v[40:41], v[34:35], v[34:35]
	v_pk_mul_f32 v[44:45], v[36:37], v[36:37]
	v_max_f32_e32 v26, v26, v26
	v_max_f32_e32 v27, v27, v27
	v_lshl_add_u64 v[50:51], v[140:141], 0, s[20:21]
	v_cvt_pk_bf16_f32 v34, v38, v39
	v_cvt_pk_bf16_f32 v35, v40, v41
	v_cvt_pk_bf16_f32 v36, v42, v43
	v_cvt_pk_bf16_f32 v37, v44, v45
	v_max_f32_e32 v26, 0, v26
	v_max_f32_e32 v27, 0, v27
	global_store_dwordx4 v[50:51], v[34:37], off offset:256
	v_max_f32_e32 v30, v30, v30
	v_max_f32_e32 v31, v31, v31
	v_pk_mul_f32 v[36:37], v[26:27], v[26:27]
	v_max_f32_e32 v27, v28, v28
	v_max_f32_e32 v30, 0, v30
	v_max_f32_e32 v31, 0, v31
	v_max_f32_e32 v26, v32, v32
	v_max_f32_e32 v28, 0, v27
	v_max_f32_e32 v27, v33, v33
	v_max_f32_e32 v29, v29, v29
	v_pk_mul_f32 v[30:31], v[30:31], v[30:31]
	v_max_f32_e32 v26, 0, v26
	v_max_f32_e32 v27, 0, v27
	v_max_f32_e32 v29, 0, v29
	s_mov_b32 s3, 0x280000
	v_pk_mul_f32 v[32:33], v[26:27], v[26:27]
	v_pk_mul_f32 v[38:39], v[28:29], v[28:29]
	v_cvt_pk_bf16_f32 v26, v30, v31
	v_add_co_u32_e32 v30, vcc, s3, v140
	v_max_f32_e32 v18, v18, v18
	v_max_f32_e32 v19, v19, v19
	v_cvt_pk_bf16_f32 v27, v32, v33
	v_cvt_pk_bf16_f32 v28, v36, v37
	v_cvt_pk_bf16_f32 v29, v38, v39
	v_addc_co_u32_e32 v31, vcc, 0, v141, vcc
	v_max_f32_e32 v18, 0, v18
	v_max_f32_e32 v19, 0, v19
	global_store_dwordx4 v[30:31], v[26:29], off
	v_max_f32_e32 v22, v22, v22
	v_max_f32_e32 v23, v23, v23
	v_pk_mul_f32 v[26:27], v[18:19], v[18:19]
	v_max_f32_e32 v19, v20, v20
	v_max_f32_e32 v18, v24, v24
	v_max_f32_e32 v20, 0, v19
	v_max_f32_e32 v19, v25, v25
	v_max_f32_e32 v21, v21, v21
	v_max_f32_e32 v22, 0, v22
	v_max_f32_e32 v23, 0, v23
	v_max_f32_e32 v18, 0, v18
	v_max_f32_e32 v19, 0, v19
	v_max_f32_e32 v21, 0, v21
	s_mov_b64 s[20:21], 0x280000
	v_pk_mul_f32 v[22:23], v[22:23], v[22:23]
	v_pk_mul_f32 v[24:25], v[18:19], v[18:19]
	v_pk_mul_f32 v[28:29], v[20:21], v[20:21]
	v_max_f32_e32 v10, v10, v10
	v_max_f32_e32 v11, v11, v11
	v_lshl_add_u64 v[34:35], v[140:141], 0, s[20:21]
	v_cvt_pk_bf16_f32 v18, v22, v23
	v_cvt_pk_bf16_f32 v19, v24, v25
	v_cvt_pk_bf16_f32 v20, v26, v27
	v_cvt_pk_bf16_f32 v21, v28, v29
	v_max_f32_e32 v10, 0, v10
	v_max_f32_e32 v11, 0, v11
	global_store_dwordx4 v[34:35], v[18:21], off offset:256
	v_max_f32_e32 v14, v14, v14
	v_max_f32_e32 v15, v15, v15
	v_pk_mul_f32 v[20:21], v[10:11], v[10:11]
	v_max_f32_e32 v11, v12, v12
	v_max_f32_e32 v14, 0, v14
	v_max_f32_e32 v15, 0, v15
	v_max_f32_e32 v10, v16, v16
	v_max_f32_e32 v12, 0, v11
	v_max_f32_e32 v11, v17, v17
	v_max_f32_e32 v13, v13, v13
	v_pk_mul_f32 v[14:15], v[14:15], v[14:15]
	v_max_f32_e32 v10, 0, v10
	v_max_f32_e32 v11, 0, v11
	v_max_f32_e32 v13, 0, v13
	s_mov_b32 s3, 0x2c0000
	v_pk_mul_f32 v[16:17], v[10:11], v[10:11]
	v_pk_mul_f32 v[22:23], v[12:13], v[12:13]
	v_cvt_pk_bf16_f32 v10, v14, v15
	v_add_co_u32_e32 v14, vcc, s3, v140
	v_max_f32_e32 v2, v2, v2
	v_max_f32_e32 v3, v3, v3
	v_cvt_pk_bf16_f32 v11, v16, v17
	v_cvt_pk_bf16_f32 v12, v20, v21
	v_cvt_pk_bf16_f32 v13, v22, v23
	v_addc_co_u32_e32 v15, vcc, 0, v141, vcc
	v_max_f32_e32 v2, 0, v2
	v_max_f32_e32 v3, 0, v3
	global_store_dwordx4 v[14:15], v[10:13], off
	v_max_f32_e32 v6, v6, v6
	v_max_f32_e32 v7, v7, v7
	v_pk_mul_f32 v[10:11], v[2:3], v[2:3]
	v_max_f32_e32 v3, v4, v4
	v_max_f32_e32 v2, v8, v8
	v_max_f32_e32 v4, 0, v3
	v_max_f32_e32 v3, v9, v9
	v_max_f32_e32 v5, v5, v5
	v_max_f32_e32 v6, 0, v6
	v_max_f32_e32 v7, 0, v7
	v_max_f32_e32 v2, 0, v2
	v_max_f32_e32 v3, 0, v3
	v_max_f32_e32 v5, 0, v5
	s_mov_b64 s[20:21], 0x2c0000
	v_pk_mul_f32 v[6:7], v[6:7], v[6:7]
	v_pk_mul_f32 v[8:9], v[2:3], v[2:3]
	v_pk_mul_f32 v[12:13], v[4:5], v[4:5]
	v_lshl_add_u64 v[18:19], v[140:141], 0, s[20:21]
	v_cvt_pk_bf16_f32 v2, v6, v7
	v_cvt_pk_bf16_f32 v3, v8, v9
	v_cvt_pk_bf16_f32 v4, v10, v11
	v_cvt_pk_bf16_f32 v5, v12, v13
	s_and_b64 vcc, exec, s[0:1]
	s_mov_b32 s16, s8
	s_mov_b32 s18, s10
	s_mov_b64 s[22:23], s[14:15]
	s_mov_b64 s[20:21], s[12:13]
	global_store_dwordx4 v[18:19], v[2:5], off offset:256
	s_cbranch_vccz .LBB0_1276
	s_waitcnt vmcnt(0)
	s_cmpk_gt_u32 s27, 0xff
	s_cbranch_scc1 .LBB0_1283
	s_barrier
